# baseline (speedup 1.0000x reference)
; __device__ void attn_a_item(const Params& p, int layer, int b, int h, int q128, unsigned char* smem) {
;     const int tid_ = otid(); const int lane = tid_ & 63, w = tid_ >> 6, l15 = lane & 15, kg = lane >> 4;
;     const int qg = w & 3, strm = w >> 2;
;     const bf16_t* proj = reinterpret_cast<const bf16_t*>(p.ws + WS_PROJ) + (size_t)b * SEQ * PW;
;     const bf16_t* kbase = proj + 256 + h * 64;
;     const bf16_t* vbase = reinterpret_cast<const bf16_t*>(p.ws + WS_VT) + ((size_t)b * VTW + h * 64) * SEQ;
;     const int fo = swz(l15 * 64 + kg * 16);
;     const TileOfs tofs = make_tile_ofs(tid_);
;     const int qw0 = q128 * 128 + qg * 32;
;     bf16x8 qf[2][2];
; #pragma unroll
;     for (int c = 0; c < 2; ++c)
; #pragma unroll
;         for (int qt = 0; qt < 2; ++qt)
;             qf[c][qt] = *reinterpret_cast<const bf16x8*>(proj + (size_t)(qw0 + qt * 16 + l15) * PW + h * 64 + c * 32 + kg * 8);
;     const float slope = exp2f(-2.f * (float)(h + 1));
;     const float slope2 = slope * LOG2E;
;     const float c2 = 0.17677669529663687f * LOG2E;
;     f32x4 o[2][2][4], ls[2][2];
;     float ub[2][2];
;     float ubm = 0.f;
;     {
;         const unsigned* km = reinterpret_cast<const unsigned*>(p.ws + WS_LAM) + SM_KMAX + layer * 16 + (b * 4 + h) * 2;
; #pragma unroll
;         for (int mp = 0; mp < 2; ++mp) {
;             const float kmaxn = sqrtf(__uint_as_float(km[mp]));
; #pragma unroll
;             for (int qt = 0; qt < 2; ++qt) {
;                 float qn = 0.f;
; #pragma unroll
;                 for (int j = 0; j < 8; ++j) { float v = __uint_as_float(((unsigned)(unsigned short)qf[mp][qt][j]) << 16); qn += v * v; }
;                 qn += __shfl_xor(qn, 16); qn += __shfl_xor(qn, 32);
;                 ub[mp][qt] = c2 * sqrtf(qn) * kmaxn * 1.02f + 0.01f;
;                 ubm = fmaxf(ubm, ub[mp][qt]);
;                 ls[mp][qt] = f32x4{0.f, 0.f, 0.f, 0.f};
; #pragma unroll
;                 for (int et = 0; et < 4; ++et) o[mp][qt][et] = f32x4{0.f, 0.f, 0.f, 0.f};
;             }
;         }
;     }
;     const float thr = 150.5f;
;     f32x4 cb[2];
;     {
;         const float sc = slope2 / c2;
; #pragma unroll
;         for (int t = 0; t < 2; ++t)
; #pragma unroll
;             for (int r = 0; r < 4; ++r) cb[t][r] = sc * (float)(t * 4 + r);
;     }
;     const int gmax = q128 * 4 + qg;
;     const int jtop = q128 * 2 + 1;
.LBB0_431:
	s_andn2_b64 vcc, exec, s[2:3]
	s_cbranch_vccnz .LBB0_383
	s_ashr_i32 s3, s28, 8
	s_and_b32 s55, s28, 1
	s_not_b32 s4, s28
	s_sub_i32 s2, 3, s3
	s_bfe_u32 s45, s4, 0x70001
	s_mul_i32 s4, s55, 0x3400000
	s_add_u32 s6, s42, s4
	v_mov_b32_e32 v172, v189
	s_addc_u32 s7, s43, 0
	s_lshl_b32 s54, s2, 6
	s_mul_i32 s4, s55, 0x280
	s_add_i32 s62, s4, s54
	s_waitcnt lgkmcnt(0)
	v_lshrrev_b32_e32 v4, 3, v172
	v_lshrrev_b32_e32 v0, 6, v172
	s_lshl_b64 s[4:5], s[62:63], 15
	v_and_b32_e32 v3, 6, v4
	v_lshrrev_b32_e32 v5, 2, v172
	s_add_u32 s46, s52, s4
	v_ashrrev_i32_e32 v2, 3, v172
	v_and_or_b32 v5, v5, 1, v3
	v_lshrrev_b32_e32 v6, 1, v172
	v_and_b32_e32 v0, 0x3ffffe, v0
	v_bfe_u32 v173, v172, 6, 2
	s_addc_u32 s47, s53, s5
	v_and_or_b32 v3, v2, -8, v5
	v_and_b32_e32 v6, 4, v6
	v_and_b32_e32 v7, 3, v172
	v_lshrrev_b32_e32 v9, 1, v2
	v_and_or_b32 v0, v4, 1, v0
	s_lshl_b32 s83, s45, 7
	s_lshl_b32 s4, s2, 7
	v_and_b32_e32 v157, 15, v172
	v_or_b32_e32 v8, v6, v7
	v_and_b32_e32 v9, 12, v9
	v_lshrrev_b32_e32 v20, 7, v172
	v_lshlrev_b32_e32 v25, 8, v6
	v_lshlrev_b32_e32 v6, 4, v7
	v_lshlrev_b32_e32 v22, 10, v0
	v_lshlrev_b32_e32 v0, 6, v3
	v_lshl_or_b32 v171, v173, 5, s83
	s_add_u32 s92, s6, s4
	v_bfe_u32 v21, v172, 5, 1
	v_and_or_b32 v5, v5, 3, v9
	v_lshlrev_b32_e32 v7, 1, v2
	v_and_or_b32 v23, v0, s64, v6
	v_lshlrev_b32_e32 v0, 2, v2
	v_or_b32_e32 v26, v171, v157
	s_addc_u32 s93, s7, 0
	v_and_or_b32 v20, v20, s94, v21
	s_sub_i32 s3, 4, s3
	v_lshlrev_b32_e32 v5, 6, v5
	v_and_b32_e32 v7, 32, v7
	v_and_b32_e32 v31, 32, v0
	v_and_b32_e32 v0, 48, v172
	v_mul_u32_u24_e32 v2, 0x680, v26
	v_lshlrev_b32_e32 v53, 11, v20
	v_cvt_f32_u32_e32 v20, s3
	v_bitop3_b32 v36, v5, v7, v6 bitop3:0x36
	v_lshl_add_u64 v[4:5], s[92:93], 0, v[0:1]
	v_lshlrev_b32_e32 v6, 1, v2
	v_mov_b32_e32 v7, v1
	v_lshl_add_u64 v[12:13], v[4:5], 0, v[6:7]
	s_mov_b32 s4, 0xd000
	v_add_co_u32_e32 v16, vcc, s4, v12
	v_mul_f32_e32 v21, -2.0, v20
	s_nop 0
	v_addc_co_u32_e32 v17, vcc, 0, v13, vcc
	s_mov_b32 s3, 0xc2fc0000
	v_cmp_gt_f32_e32 vcc, s3, v21
	s_and_b64 s[4:5], vcc, exec
	s_cselect_b32 s3, 0xffffffc0, 0
	v_cndmask_b32_e32 v21, 0, v210, vcc
	v_fmac_f32_e32 v21, -2.0, v20
	v_exp_f32_e32 v20, v21
	v_and_b32_e32 v21, 64, v208
	v_add_u32_e32 v21, 64, v21
	s_lshl_b32 s2, s2, 1
	v_ldexp_f32 v54, v20, s3
	v_xor_b32_e32 v20, 16, v208
	s_lshl_b32 s3, s55, 3
	v_cmp_lt_i32_e32 vcc, v20, v21
	s_add_i32 s62, s2, s3
	s_lshl_b64 s[2:3], s[62:63], 2
	v_cndmask_b32_e32 v20, v208, v20, vcc
	v_lshlrev_b32_e32 v170, 2, v20
	v_xor_b32_e32 v20, 32, v208
	s_add_u32 s2, s72, s2
	v_cmp_lt_i32_e32 vcc, v20, v21
	s_addc_u32 s3, s81, s3
	v_lshlrev_b32_e32 v24, 3, v8
	v_cndmask_b32_e32 v20, v208, v20, vcc
	global_load_dwordx4 v[4:7], v[12:13], off
	global_load_dwordx4 v[8:11], v[16:17], off
	s_nop 0
	global_load_dwordx4 v[12:15], v[12:13], off offset:64
	s_nop 0
	global_load_dwordx4 v[16:19], v[16:17], off offset:64
	v_lshlrev_b32_e32 v169, 2, v20
	global_load_dwordx2 v[20:21], v1, s[2:3]
	v_mul_f32_e32 v176, 0x3fb8aa3b, v54
	s_mov_b32 s62, 0xc3168000
	v_or3_b32 v175, v53, v25, v36
	v_mul_lo_u32 v2, v3, s82
	v_or_b32_e32 v2, v2, v24
	v_lshl_or_b32 v24, v3, 14, v24
	v_cvt_f32_u32_e32 v3, s83
	s_lshl_b32 s64, s45, 1
	s_or_b32 s82, s64, 1
	v_bitop3_b32 v177, v31, v22, v23 bitop3:0xde
	v_mov_b32_e32 v240, v2
	v_ashrrev_i32_e32 v241, 31, v2
	v_mov_b32_e32 v242, v24
	v_ashrrev_i32_e32 v243, 31, v24
	v_lshlrev_b64 v[70:71], 1, v[240:241]
	v_lshlrev_b64 v[72:73], 1, v[242:243]
	s_mov_b32 s101, 0
	s_mul_i32 s100, s82, 0x34000
	s_add_u32 s94, s92, s100
	s_addc_u32 s95, s93, 0
	s_lshl_b32 s100, s82, 7
	v_lshl_add_u64 v[244:245], s[94:95], 0, v[70:71]
	s_add_u32 s94, s46, s100
	s_addc_u32 s95, s47, 0
	s_max_u32 s100, s64, 1
	s_lshl_b32 s100, s100, 6
	s_sub_i32 s100, s100, 64
	global_load_dwordx4 v[54:57], v[244:245], off offset:512
	v_lshl_add_u64 v[244:245], s[94:95], 0, v[72:73]
	s_mul_i32 s94, s100, 0xd00
	s_mul_hi_u32 s83, s100, 0xd00
	s_add_u32 s94, s92, s94
	s_addc_u32 s95, s93, s83
	global_load_dwordx4 v[58:61], v[244:245], off
	v_lshl_add_u64 v[244:245], s[94:95], 0, v[70:71]
	s_lshl_b64 s[94:95], s[100:101], 1
	s_add_u32 s94, s46, s94
	s_addc_u32 s95, s47, s95
	global_load_dwordx4 v[62:65], v[244:245], off offset:512
	v_lshl_add_u64 v[244:245], s[94:95], 0, v[72:73]
	global_load_dwordx4 v[66:69], v[244:245], off
	s_mul_i32 s100, s45, 0x68000
	s_add_u32 s94, s92, s100
	s_addc_u32 s95, s93, 0
	s_lshl_b32 s100, s45, 8
	v_lshl_add_u64 v[244:245], s[94:95], 0, v[70:71]
	s_add_u32 s94, s46, s100
	s_addc_u32 s95, s47, 0
	s_max_u32 s100, s64, 2
	s_lshl_b32 s100, s100, 6
	s_addk_i32 s100, 0xff80
	s_mul_hi_u32 s83, s100, 0xd00
	v_lshl_add_u64 v[246:247], s[94:95], 0, v[72:73]
	s_mul_i32 s94, s100, 0xd00
	s_add_u32 s94, s92, s94
	s_addc_u32 s95, s93, s83
	v_lshl_add_u64 v[248:249], s[94:95], 0, v[70:71]
	s_lshl_b64 s[94:95], s[100:101], 1
	global_load_dwordx4 v[224:227], v[244:245], off offset:512
	s_add_u32 s94, s46, s94
	global_load_dwordx4 v[228:231], v[246:247], off
	s_addc_u32 s95, s47, s95
	global_load_dwordx4 v[232:235], v[248:249], off offset:512
	v_lshl_add_u64 v[250:251], s[94:95], 0, v[72:73]
	global_load_dwordx4 v[236:239], v[250:251], off
	s_waitcnt vmcnt(11)
	v_and_b32_e32 v37, 0xffff0000, v8
	v_and_b32_e32 v32, 0xffff0000, v4
	v_mul_f32_e32 v32, v32, v32
	v_mul_f32_e32 v37, v37, v37
	s_waitcnt vmcnt(8)
; __device__ void attn_a_item(const Params& p, int layer, int b, int h, int q128, unsigned char* smem) {
;     ...
;     {
;         const unsigned* km = reinterpret_cast<const unsigned*>(p.ws + WS_LAM) + SM_KMAX + layer * 16 + (b * 4 + h) * 2;
; #pragma unroll
;         for (int mp = 0; mp < 2; ++mp) {
;             const float kmaxn = sqrtf(__uint_as_float(km[mp]));
; #pragma unroll
;             for (int qt = 0; qt < 2; ++qt) {
;                 float qn = 0.f;
; #pragma unroll
;                 for (int j = 0; j < 8; ++j) { float v = __uint_as_float(((unsigned)(unsigned short)qf[mp][qt][j]) << 16); qn += v * v; }
;                 qn += __shfl_xor(qn, 16); qn += __shfl_xor(qn, 32);
;                 ub[mp][qt] = c2 * sqrtf(qn) * kmaxn * 1.02f + 0.01f;
;                 ubm = fmaxf(ubm, ub[mp][qt]);
;                 ls[mp][qt] = f32x4{0.f, 0.f, 0.f, 0.f};
; #pragma unroll
;                 for (int et = 0; et < 4; ++et) o[mp][qt][et] = f32x4{0.f, 0.f, 0.f, 0.f};
;             }
;         }
;     }
;     const float thr = 150.5f;
;     f32x4 cb[2];
;     {
;         const float sc = slope2 / c2;
; #pragma unroll
;         for (int t = 0; t < 2; ++t)
; #pragma unroll
;             for (int r = 0; r < 4; ++r) cb[t][r] = sc * (float)(t * 4 + r);
;     }
;     const int gmax = q128 * 4 + qg;
;     const int jtop = q128 * 2 + 1;
;     const int jlow = max(0, (int)floorf(((float)(q128 * 128) - thr / slope2) * (1.f / 64.f)) - 1);
;     const int nsteps = (jtop - jlow + 4) / 4;
;     TileRegs tr0, tr1;
;     auto tl = [&](int j) { return (j > 0 ? j : 0) * 64; };
;     attn_tile_load(tr0, kbase, vbase, tl(jtop), tofs);
;     attn_tile_load(tr1, kbase, vbase, tl(jtop - 2), tofs);
;     attn_tile_store(tr0, smem, tofs);
;     attn_tile_store(tr1, smem + 32768, tofs);
;     attn_tile_load(tr0, kbase, vbase, tl(jtop - 1), tofs);
;     attn_tile_load(tr1, kbase, vbase, tl(jtop - 3), tofs);
;     attn_tile_store(tr0, smem + 16384, tofs);
;     attn_tile_store(tr1, smem + 49152, tofs);
;     __syncthreads();
	v_cmp_gt_f32_e64 s[2:3], s49, v20
	v_mul_f32_e32 v27, 0x4f800000, v20
	v_cmp_gt_f32_e64 s[16:17], s49, v21
	v_cndmask_b32_e64 v27, v20, v27, s[2:3]
	v_sqrt_f32_e32 v28, v27
	s_nop 0
	v_add_u32_e32 v29, -1, v28
	v_fma_f32 v20, -v29, v28, v27
	v_add_u32_e32 v30, 1, v28
	v_cmp_ge_f32_e64 s[4:5], 0, v20
	v_fma_f32 v20, -v30, v28, v27
	v_cmp_lt_f32_e64 s[6:7], 0, v20
	v_lshlrev_b32_e32 v20, 16, v4
	v_fmac_f32_e32 v32, v20, v20
	v_lshlrev_b32_e32 v20, 16, v5
	v_fmac_f32_e32 v32, v20, v20
	v_and_b32_e32 v20, 0xffff0000, v5
	v_fmac_f32_e32 v32, v20, v20
	v_lshlrev_b32_e32 v20, 16, v6
	v_fmac_f32_e32 v32, v20, v20
	v_and_b32_e32 v20, 0xffff0000, v6
	v_fmac_f32_e32 v32, v20, v20
	v_lshlrev_b32_e32 v20, 16, v7
	v_fmac_f32_e32 v32, v20, v20
	v_and_b32_e32 v20, 0xffff0000, v7
	v_fmac_f32_e32 v32, v20, v20
	ds_bpermute_b32 v20, v170, v32
	s_waitcnt lgkmcnt(0)
	v_add_f32_e32 v20, v32, v20
	ds_bpermute_b32 v32, v169, v20
	s_waitcnt lgkmcnt(0)
	v_add_f32_e32 v20, v20, v32
	v_cmp_gt_f32_e64 s[8:9], s49, v20
	v_mul_f32_e32 v32, 0x4f800000, v20
	s_nop 0
	v_cndmask_b32_e64 v32, v20, v32, s[8:9]
	v_sqrt_f32_e32 v33, v32
	s_nop 0
	v_add_u32_e32 v34, -1, v33
	v_fma_f32 v20, -v34, v33, v32
	v_add_u32_e32 v35, 1, v33
	v_cmp_ge_f32_e64 s[10:11], 0, v20
	v_fma_f32 v20, -v35, v33, v32
	v_cmp_lt_f32_e64 s[12:13], 0, v20
	v_lshlrev_b32_e32 v20, 16, v8
	v_fmac_f32_e32 v37, v20, v20
	v_lshlrev_b32_e32 v20, 16, v9
	v_fmac_f32_e32 v37, v20, v20
	v_and_b32_e32 v20, 0xffff0000, v9
	v_fmac_f32_e32 v37, v20, v20
	v_lshlrev_b32_e32 v20, 16, v10
	v_fmac_f32_e32 v37, v20, v20
	v_and_b32_e32 v20, 0xffff0000, v10
	v_fmac_f32_e32 v37, v20, v20
	v_lshlrev_b32_e32 v20, 16, v11
	v_fmac_f32_e32 v37, v20, v20
	v_and_b32_e32 v20, 0xffff0000, v11
	v_fmac_f32_e32 v37, v20, v20
	ds_bpermute_b32 v20, v170, v37
	s_waitcnt lgkmcnt(0)
	v_add_f32_e32 v20, v37, v20
	ds_bpermute_b32 v37, v169, v20
	s_waitcnt lgkmcnt(0)
	v_add_f32_e32 v20, v20, v37
	v_cmp_gt_f32_e64 s[14:15], s49, v20
	v_mul_f32_e32 v37, 0x4f800000, v20
	s_nop 0
	v_cndmask_b32_e64 v37, v20, v37, s[14:15]
	v_sqrt_f32_e32 v38, v37
	s_nop 0
	v_add_u32_e32 v39, -1, v38
	v_fma_f32 v20, -v39, v38, v37
	v_add_u32_e32 v41, 1, v38
	v_cmp_ge_f32_e64 s[18:19], 0, v20
	v_fma_f32 v20, -v41, v38, v37
	v_cmp_lt_f32_e64 s[20:21], 0, v20
	v_mul_f32_e32 v20, 0x4f800000, v21
	v_cndmask_b32_e64 v40, v21, v20, s[16:17]
	v_sqrt_f32_e32 v42, v40
	v_and_b32_e32 v21, 0xffff0000, v12
	v_mul_f32_e32 v21, v21, v21
	v_add_u32_e32 v43, -1, v42
	v_fma_f32 v20, -v43, v42, v40
	v_add_u32_e32 v44, 1, v42
	v_cmp_ge_f32_e64 s[22:23], 0, v20
	v_fma_f32 v20, -v44, v42, v40
	v_cmp_lt_f32_e64 s[24:25], 0, v20
	v_lshlrev_b32_e32 v20, 16, v12
	v_fmac_f32_e32 v21, v20, v20
	v_lshlrev_b32_e32 v20, 16, v13
	v_fmac_f32_e32 v21, v20, v20
	v_and_b32_e32 v20, 0xffff0000, v13
	v_fmac_f32_e32 v21, v20, v20
	v_lshlrev_b32_e32 v20, 16, v14
	v_fmac_f32_e32 v21, v20, v20
	v_and_b32_e32 v20, 0xffff0000, v14
	v_fmac_f32_e32 v21, v20, v20
	v_lshlrev_b32_e32 v20, 16, v15
	v_fmac_f32_e32 v21, v20, v20
	v_and_b32_e32 v20, 0xffff0000, v15
	v_fmac_f32_e32 v21, v20, v20
	ds_bpermute_b32 v20, v170, v21
	s_waitcnt lgkmcnt(0)
	v_add_f32_e32 v20, v21, v20
	ds_bpermute_b32 v21, v169, v20
	s_waitcnt lgkmcnt(0)
	v_add_f32_e32 v20, v20, v21
	v_cmp_gt_f32_e64 s[26:27], s49, v20
	v_mul_f32_e32 v21, 0x4f800000, v20
	s_nop 0
	v_cndmask_b32_e64 v45, v20, v21, s[26:27]
	v_sqrt_f32_e32 v46, v45
	v_and_b32_e32 v21, 0xffff0000, v16
	v_mul_f32_e32 v21, v21, v21
	v_add_u32_e32 v47, -1, v46
	v_fma_f32 v20, -v47, v46, v45
	v_add_u32_e32 v48, 1, v46
	v_cmp_ge_f32_e64 s[28:29], 0, v20
	v_fma_f32 v20, -v48, v46, v45
	v_cmp_lt_f32_e64 s[30:31], 0, v20
	v_lshlrev_b32_e32 v20, 16, v16
	v_fmac_f32_e32 v21, v20, v20
	v_lshlrev_b32_e32 v20, 16, v17
	v_fmac_f32_e32 v21, v20, v20
	v_and_b32_e32 v20, 0xffff0000, v17
	v_fmac_f32_e32 v21, v20, v20
	v_lshlrev_b32_e32 v20, 16, v18
	v_fmac_f32_e32 v21, v20, v20
	v_and_b32_e32 v20, 0xffff0000, v18
	v_fmac_f32_e32 v21, v20, v20
	v_lshlrev_b32_e32 v20, 16, v19
	v_fmac_f32_e32 v21, v20, v20
	v_and_b32_e32 v20, 0xffff0000, v19
	v_fmac_f32_e32 v21, v20, v20
	ds_bpermute_b32 v20, v170, v21
	s_waitcnt lgkmcnt(0)
	v_add_f32_e32 v20, v21, v20
	ds_bpermute_b32 v21, v169, v20
	s_waitcnt lgkmcnt(0)
	v_add_f32_e32 v20, v20, v21
	v_cmp_gt_f32_e64 s[34:35], s49, v20
	v_mul_f32_e32 v21, 0x4f800000, v20
	s_nop 0
	v_cndmask_b32_e64 v49, v20, v21, s[34:35]
	v_sqrt_f32_e32 v50, v49
	s_nop 0
	v_add_u32_e32 v51, -1, v50
	v_fma_f32 v20, -v51, v50, v49
	v_add_u32_e32 v52, 1, v50
	v_cmp_ge_f32_e64 s[36:37], 0, v20
	v_fma_f32 v20, -v52, v50, v49
	v_cmp_lt_f32_e64 s[38:39], 0, v20
	v_div_scale_f32 v20, s[94:95], v176, v176, s62
	v_rcp_f32_e32 v21, v20
	s_nop 0
	v_fma_f32 v25, -v20, v21, 1.0
	v_fmac_f32_e32 v21, v25, v21
	v_div_scale_f32 v25, vcc, s62, v176, s62
	v_mul_f32_e32 v36, v25, v21
	v_fma_f32 v53, -v20, v36, v25
	v_fmac_f32_e32 v36, v53, v21
	v_fma_f32 v20, -v20, v36, v25
	v_div_fmas_f32 v20, v20, v21, v36
	v_div_fixup_f32 v20, v20, v176, s62
	v_add_f32_e32 v3, v3, v20
	v_mul_f32_e32 v3, 0x3c800000, v3
	v_floor_f32_e32 v3, v3
	v_cvt_i32_f32_e32 v3, v3
	s_mul_i32 s62, s82, 0x34000
	s_add_u32 s94, s92, s62
	s_addc_u32 s95, s93, 0
	v_readfirstlane_b32 s65, v3
	v_ashrrev_i32_e32 v3, 31, v2
	v_ashrrev_i32_e32 v25, 31, v24
	v_readfirstlane_b32 s62, v172
	s_cmpk_gt_i32 s62, 0xff
	s_cselect_b64 s[94:95], -1, 0
	s_waitcnt vmcnt(7)
	ds_write_b128 v175, v[54:57]
	s_waitcnt vmcnt(6)
	ds_write_b128 v177, v[58:61] offset:8192
	s_waitcnt vmcnt(5)
	ds_write_b128 v175, v[62:65] offset:32768
	s_waitcnt vmcnt(4)
	ds_write_b128 v177, v[66:69] offset:40960
	s_waitcnt vmcnt(3)
	ds_write_b128 v175, v[224:227] offset:16384
	s_waitcnt vmcnt(2)
	ds_write_b128 v177, v[228:231] offset:24576
	s_waitcnt vmcnt(1)
	ds_write_b128 v175, v[232:235] offset:49152
	s_waitcnt vmcnt(0)
	ds_write_b128 v177, v[236:239] offset:57344
	s_cmpk_lt_i32 s62, 0x100
	s_waitcnt lgkmcnt(0)
	s_barrier
	s_cbranch_scc1 .LBB0_434
	s_setprio 1
